# branch_a_prep: conv-weight loads issued before the PA-data wait, vmcnt(0) -> counted vmcnt(6)
# speedup vs baseline: 1.0118x; 1.0042x over previous
; __device__ __forceinline__ unsigned pk2(float lo, float hi) { unsigned r; asm volatile("v_cvt_pk_bf16_f32 %0, %1, %2" : "=v"(r) : "v"(lo), "v"(hi)); return r; }
; __device__ __forceinline__ void unpack8(const u32x4 w, float* o) { o[0] = bflo(w.x); o[1] = bfhi(w.x); o[2] = bflo(w.y); o[3] = bfhi(w.y); o[4] = bflo(w.z); o[5] = bfhi(w.z); o[6] = bflo(w.w); o[7] = bfhi(w.w); }
; __device__ __forceinline__ int ltid() { int t = threadIdx.x; asm volatile("" : "+v"(t)); return t; }
; __device__ __forceinline__ void branch_a_prep(const bf16_t* __restrict__ PA, const float* __restrict__ cw  , bf16_t* __restrict__ AA) {
;     ...
;     for (int idx = blockIdx.x * 512 + ltid(); idx < L_ * 64; idx += gridDim.x * 512) {
;         const int t = idx >> 6, c8 = (idx & 63) * 8;
;         const bf16_t* row = PA + (size_t)t * 3072 + c8;
;         const u32x4 z4 = (u32x4){0u, 0u, 0u, 0u};
;         const u32x4 xa0 = *(const u32x4*)row, ba0 = *(const u32x4*)(row + 512), ca0 = *(const u32x4*)(row + 1024);
;         const u32x4 xam = t > 0 ? *(const u32x4*)(row - 3072) : z4, cam = t > 0 ? *(const u32x4*)(row - 3072 + 1024) : z4;
;         const u32x4 xap = t < L_ - 1 ? *(const u32x4*)(row + 3072) : z4, cap = t < L_ - 1 ? *(const u32x4*)(row + 3072 + 1024) : z4;
;         float x0[8], b0[8], c0[8], xm[8], cm[8], xp[8], cp[8];
;         unpack8(xa0, x0); unpack8(ba0, b0); unpack8(ca0, c0); unpack8(xam, xm); unpack8(cam, cm); unpack8(xap, xp); unpack8(cap, cp);
;         float w0[8], w1[8], w2[8];
;         *(float4*)(w0) = *(const float4*)(cw + c8); *(float4*)(w0 + 4) = *(const float4*)(cw + c8 + 4);
;         *(float4*)(w1) = *(const float4*)(cw + 512 + c8); *(float4*)(w1 + 4) = *(const float4*)(cw + 512 + c8 + 4);
;         *(float4*)(w2) = *(const float4*)(cw + 1024 + c8); *(float4*)(w2 + 4) = *(const float4*)(cw + 1024 + c8 + 4);
;         float o[8];
; #pragma unroll
;         for (int e = 0; e < 8; ++e) o[e] = b0[e] * (w0[e] * (cm[e] * xm[e]) + w1[e] * (c0[e] * x0[e]) + w2[e] * (cp[e] * xp[e]));
;         u32x4 w; w.x = pk2(o[0], o[1]); w.y = pk2(o[2], o[3]); w.z = pk2(o[4], o[5]); w.w = pk2(o[6], o[7]);
;         *(u32x4*)(AA + (size_t)t * 512 + c8) = w;
.LBB0_204:
	s_or_b64 exec, exec, s[2:3]
	v_readlane_b32 s0, v246, 21
	v_lshlrev_b32_e32 v30, 2, v34
	v_readlane_b32 s1, v246, 22
	v_readlane_b32 s2, v246, 23
	v_readlane_b32 s3, v246, 24
	s_nop 4
	global_load_dwordx4 v[34:37], v30, s[0:1]
	global_load_dwordx4 v[38:41], v30, s[2:3]
	global_load_dwordx4 v[42:45], v30, s[0:1] offset:16
	global_load_dwordx4 v[46:49], v30, s[2:3] offset:16
	global_load_dwordx4 v[50:53], v30, s[0:1] offset:2048
	global_load_dwordx4 v[54:57], v30, s[0:1] offset:2064
	s_waitcnt vmcnt(6)
	v_lshlrev_b32_e32 v66, 16, v24
	v_and_b32_e32 v67, 0xffff0000, v24
	v_lshlrev_b32_e32 v68, 16, v25
	v_and_b32_e32 v69, 0xffff0000, v25
	v_lshlrev_b32_e32 v70, 16, v26
	v_and_b32_e32 v71, 0xffff0000, v26
	v_lshlrev_b32_e32 v72, 16, v27
	v_and_b32_e32 v73, 0xffff0000, v27
	v_lshlrev_b32_e32 v74, 16, v4
	s_waitcnt vmcnt(6)
	v_lshlrev_b32_e32 v75, 16, v8
	v_lshlrev_b32_e32 v25, 16, v20
	v_lshlrev_b32_e32 v24, 16, v12
	v_lshlrev_b32_e32 v27, 16, v16
	v_lshlrev_b32_e32 v26, 16, v0
	v_and_b32_e32 v76, 0xffff0000, v8
	v_and_b32_e32 v77, 0xffff0000, v4
	v_and_b32_e32 v30, 0xffff0000, v12
	v_and_b32_e32 v58, 0xffff0000, v0
	v_lshlrev_b32_e32 v78, 16, v5
	v_lshlrev_b32_e32 v79, 16, v9
	v_lshlrev_b32_e32 v60, 16, v13
	v_lshlrev_b32_e32 v62, 16, v1
	v_and_b32_e32 v80, 0xffff0000, v9
	v_and_b32_e32 v81, 0xffff0000, v5
	v_and_b32_e32 v5, 0xffff0000, v21
	v_and_b32_e32 v4, 0xffff0000, v13
	v_and_b32_e32 v9, 0xffff0000, v17
	v_and_b32_e32 v8, 0xffff0000, v1
	v_lshlrev_b32_e32 v1, 16, v22
	v_lshlrev_b32_e32 v0, 16, v14
	v_lshlrev_b32_e32 v13, 16, v18
	v_lshlrev_b32_e32 v12, 16, v2
	v_and_b32_e32 v31, 0xffff0000, v20
	v_and_b32_e32 v59, 0xffff0000, v16
	v_lshlrev_b32_e32 v61, 16, v21
	v_lshlrev_b32_e32 v63, 16, v17
	v_lshlrev_b32_e32 v82, 16, v6
	v_lshlrev_b32_e32 v83, 16, v10
	v_pk_mul_f32 v[16:17], v[24:25], v[26:27]
	v_pk_mul_f32 v[4:5], v[4:5], v[8:9]
	v_pk_mul_f32 v[0:1], v[0:1], v[12:13]
	v_pk_mul_f32 v[20:21], v[30:31], v[58:59]
	v_pk_mul_f32 v[24:25], v[60:61], v[62:63]
	v_mul_f32_e32 v31, v80, v81
	v_mul_f32_e32 v58, v83, v82
	v_and_b32_e32 v10, 0xffff0000, v10
	v_and_b32_e32 v6, 0xffff0000, v6
	v_mul_f32_e32 v74, v75, v74
	v_mul_f32_e32 v75, v76, v77
	v_mul_f32_e32 v30, v79, v78
	v_mul_f32_e32 v6, v10, v6
	v_readlane_b32 s0, v246, 19
	v_readlane_b32 s1, v246, 20
	v_add_u32_e32 v32, s44, v32
	v_add_u32_e32 v33, s45, v33
	s_waitcnt vmcnt(4)
	v_mov_b32_e32 v13, v40
	s_waitcnt vmcnt(3)
	v_mov_b32_e32 v26, v42
	s_waitcnt vmcnt(2)
	v_mov_b32_e32 v27, v46
	v_mov_b32_e32 v40, v37
	v_mov_b32_e32 v8, v34
	v_mov_b32_e32 v9, v38
	v_mov_b32_e32 v38, v35
	v_mov_b32_e32 v12, v36
	v_pk_mul_f32 v[4:5], v[4:5], v[40:41]
	v_pk_mul_f32 v[0:1], v[0:1], v[26:27]
	v_pk_mul_f32 v[8:9], v[16:17], v[8:9]
	v_pk_mul_f32 v[16:17], v[20:21], v[38:39]
	v_pk_mul_f32 v[12:13], v[24:25], v[12:13]
	s_waitcnt vmcnt(1)
	v_fma_f32 v4, v31, v53, v4
	s_waitcnt vmcnt(0)
	v_fma_f32 v0, v58, v54, v0
	v_fma_f32 v8, v74, v50, v8
	v_fma_f32 v10, v75, v51, v16
	v_fma_f32 v12, v30, v52, v12
	v_add_f32_e32 v4, v4, v5
	v_add_f32_e32 v0, v0, v1
	v_add_f32_e32 v8, v8, v9
	v_add_f32_e32 v9, v10, v17
	v_add_f32_e32 v10, v12, v13
	v_mul_f32_e32 v12, v4, v69
	v_mul_f32_e32 v13, v0, v70
	v_and_b32_e32 v1, 0xffff0000, v22
	v_and_b32_e32 v0, 0xffff0000, v14
	v_and_b32_e32 v5, 0xffff0000, v18
	v_and_b32_e32 v4, 0xffff0000, v2
	v_pk_mul_f32 v[0:1], v[0:1], v[4:5]
	v_mov_b32_e32 v46, v43
	v_pk_mul_f32 v[0:1], v[0:1], v[46:47]
	v_lshlrev_b32_e32 v4, 16, v3
	v_fma_f32 v0, v6, v55, v0
	v_add_f32_e32 v0, v0, v1
	v_mul_f32_e32 v2, v0, v71
	v_lshlrev_b32_e32 v0, 16, v7
	v_lshlrev_b32_e32 v1, 16, v11
	v_mul_f32_e32 v6, v1, v0
	v_lshlrev_b32_e32 v0, 16, v15
	v_lshlrev_b32_e32 v1, 16, v23
	v_lshlrev_b32_e32 v5, 16, v19
	v_pk_mul_f32 v[0:1], v[0:1], v[4:5]
	v_mov_b32_e32 v4, v44
	v_mov_b32_e32 v5, v48
	v_pk_mul_f32 v[0:1], v[0:1], v[4:5]
	v_and_b32_e32 v5, 0xffff0000, v19
	v_fma_f32 v0, v6, v56, v0
	v_add_f32_e32 v0, v0, v1
	v_mul_f32_e32 v6, v0, v72
	v_and_b32_e32 v0, 0xffff0000, v11
	v_and_b32_e32 v1, 0xffff0000, v7
	v_mul_f32_e32 v7, v0, v1
	v_and_b32_e32 v1, 0xffff0000, v23
	v_and_b32_e32 v0, 0xffff0000, v15
	v_and_b32_e32 v4, 0xffff0000, v3
	v_pk_mul_f32 v[0:1], v[0:1], v[4:5]
	v_mov_b32_e32 v48, v45
	v_pk_mul_f32 v[0:1], v[0:1], v[48:49]
	v_lshlrev_b64 v[4:5], 10, v[28:29]
	v_fma_f32 v0, v7, v57, v0
	v_lshl_add_u64 v[4:5], s[0:1], 0, v[4:5]
	s_mov_b32 s0, 0xfffff
	v_add_f32_e32 v0, v0, v1
	v_cmp_lt_i32_e32 vcc, s0, v32
	v_mul_f32_e32 v3, v0, v73
	v_lshl_add_u64 v[4:5], v[4:5], 0, v[64:65]
	s_or_b64 s[6:7], vcc, s[6:7]
	v_mul_f32_e32 v8, v8, v66
	v_mul_f32_e32 v9, v9, v67
	v_mul_f32_e32 v10, v10, v68
	v_cvt_pk_bf16_f32 v0, v8, v9
	v_cvt_pk_bf16_f32 v1, v10, v12
	v_cvt_pk_bf16_f32 v2, v13, v2
	v_cvt_pk_bf16_f32 v3, v6, v3
	global_store_dwordx4 v[4:5], v[0:3], off
	s_andn2_b64 exec, exec, s[6:7]
	s_cbranch_execz .LBB0_213
